# mixer-A near and far softmax: bias-table LDS reads hoisted to the top of each tile body into spare registers (single wait) instead of 8 serialized read-wait groups
# speedup vs baseline: 1.0466x; 1.0096x over previous
; #define MFMA32(a, b, c) __builtin_amdgcn_mfma_f32_32x32x16_bf16((a), (b), (c), 0, 0, 0)
; template <int MODE, int NQ, int TS, bool FAST = false> ...
;     ...
;   auto QK = [&](int slot) {
;     const char* kb_ = lds + slot * 16384;
; #pragma unroll
;     for (int nq = 0; nq < NQ; ++nq)
; #pragma unroll
;       for (int r = 0; r < 16; ++r) { s[nq][0][r] = 0.f; s[nq][1][r] = 0.f; }
; #pragma unroll
;     for (int ks = 0; ks < 4; ++ks) {
;       const bf16x8 k0 = *(const bf16x8*)(kb_ + kfo4[ks]), k1 = *(const bf16x8*)(kb_ + kfo4[ks] + 4096);
; #pragma unroll
;       for (int nq = 0; nq < NQ; ++nq) { s[nq][0] = MFMA32(k0, qf[nq][ks], s[nq][0]); s[nq][1] = MFMA32(k1, qf[nq][ks], s[nq][1]); }
;     }
;   };
;   auto SM = [&](int kt) {
; #pragma unroll
;     for (int nq = 0; nq < NQ; ++nq) {
;       f32x16& s0 = s[nq][0]; f32x16& s1 = s[nq][1];
;       float mx = -1e30f;
;       if (MODE == 1) {
;       } else if (MODE == 0 || MODE == 3) {
;         const float* tb = (const float*)(lds + TAB_OFF) + (kt * 64 + 4 * hh - (q0w + 32 * nq + r32) + TAB_ZERO);
; #pragma unroll
;         for (int r = 0; r < 16; ++r) {
;           const float va = fmaf(s0[r], C2, tb[(r & 3) + 8 * (r >> 2)]), vb = fmaf(s1[r], C2, tb[(r & 3) + 8 * (r >> 2) + 32]);
;           s0[r] = va; s1[r] = vb; mx = fmaxf(mx, fmaxf(va, vb));
;         }
.LBB0_284:
	s_min_i32 s9, s6, s5
	s_cmp_gt_i32 s0, 1
	s_mov_b32 s8, s0
	s_cselect_b32 s0, -2, 4
	s_add_i32 s13, s0, s8
	v_mad_i64_i32 v[2:3], s[0:1], s9, v235, v[98:99]
	s_lshl_b32 s0, s13, 14
	s_add_i32 s13, s16, s0
	v_lshl_add_u64 v[2:3], v[2:3], 0, s[60:61]
	s_mov_b32 m0, s13
	s_nop 0
	global_load_lds_dwordx4 v[2:3], off
	v_mad_i64_i32 v[2:3], s[0:1], s9, v235, v[100:101]
	v_lshl_add_u64 v[2:3], v[2:3], 0, s[58:59]
	s_add_i32 m0, s13, 0x2000
	s_add_i32 s9, s7, 64
	global_load_lds_dwordx4 v[2:3], off
	s_add_i32 s0, s7, 0x7f
	v_cmp_ge_i32_e32 vcc, s0, v107
	v_cmp_le_i32_e64 s[0:1], s9, v108
	s_and_b64 s[78:79], vcc, s[0:1]
	s_and_saveexec_b64 s[0:1], s[38:39]
	s_xor_b64 s[0:1], exec, s[0:1]
	s_cbranch_execz .LBB0_290
	s_and_saveexec_b64 s[80:81], s[78:79]
	s_cbranch_execz .LBB0_289
	ds_read2_b32 v[116:117], v113 offset0:40 offset1:41
	ds_read2_b32 v[118:119], v113 offset1:1
	ds_read2_b32 v[120:121], v113 offset0:32 offset1:33
	ds_read2_b32 v[122:123], v113 offset0:34 offset1:35
	ds_read2_b32 v[124:125], v113 offset0:2 offset1:3
	ds_read2_b32 v[126:127], v113 offset0:42 offset1:43
	ds_read2_b32 v[128:129], v113 offset0:8 offset1:9
	ds_read2_b32 v[130:131], v113 offset0:10 offset1:11
	ds_read2_b32 v[132:133], v113 offset0:48 offset1:49
	ds_read2_b32 v[134:135], v113 offset0:16 offset1:17
	ds_read2_b32 v[136:137], v113 offset0:50 offset1:51
	ds_read2_b32 v[138:139], v113 offset0:18 offset1:19
	ds_read2_b32 v[140:141], v113 offset0:24 offset1:25
	ds_read2_b32 v[142:143], v113 offset0:56 offset1:57
	ds_read2_b32 v[144:145], v113 offset0:26 offset1:27
	ds_read2_b32 v[146:147], v113 offset0:58 offset1:59
	s_lshl_b32 s13, s8, 14
	v_or_b32_e32 v0, s13, v111
	ds_read_b128 v[2:5], v0
	ds_read_b128 v[6:9], v0 offset:4096
	v_or_b32_e32 v0, s13, v110
	s_waitcnt lgkmcnt(0)
	v_mfma_f32_32x32x16_bf16 v[64:79], v[2:5], v[80:83], 0
	v_mfma_f32_32x32x16_bf16 v[48:63], v[6:9], v[80:83], 0
	ds_read_b128 v[2:5], v0
	ds_read_b128 v[6:9], v0 offset:4096
	v_or_b32_e32 v0, s13, v109
	s_waitcnt lgkmcnt(0)
	v_mfma_f32_32x32x16_bf16 v[64:79], v[2:5], v[84:87], v[64:79]
	v_mfma_f32_32x32x16_bf16 v[48:63], v[6:9], v[84:87], v[48:63]
	ds_read_b128 v[2:5], v0
	ds_read_b128 v[6:9], v0 offset:4096
	v_or_b32_e32 v0, s13, v97
	s_waitcnt lgkmcnt(0)
	v_mfma_f32_32x32x16_bf16 v[64:79], v[2:5], v[88:91], v[64:79]
	v_mfma_f32_32x32x16_bf16 v[48:63], v[6:9], v[88:91], v[48:63]
	ds_read_b128 v[2:5], v0
	ds_read_b128 v[6:9], v0 offset:4096
	s_waitcnt lgkmcnt(0)
	v_mfma_f32_32x32x16_bf16 v[64:79], v[2:5], v[92:95], v[64:79]
	v_mfma_f32_32x32x16_bf16 v[48:63], v[6:9], v[92:95], v[48:63]
	s_nop 10
	v_fmamk_f32 v0, v64, 0x3e38aa3b, v118
	v_fmamk_f32 v3, v65, 0x3e38aa3b, v119
	v_fmamk_f32 v2, v48, 0x3e38aa3b, v120
	v_fmamk_f32 v5, v49, 0x3e38aa3b, v121
	v_max_f32_e32 v4, v0, v2
	v_max_f32_e32 v6, v3, v5
	v_max3_f32 v10, v4, s25, v6
	v_fmamk_f32 v9, v51, 0x3e38aa3b, v123
	v_fmamk_f32 v13, v53, 0x3e38aa3b, v117
	v_fmamk_f32 v4, v66, 0x3e38aa3b, v124
	v_fmamk_f32 v6, v50, 0x3e38aa3b, v122
	v_fmamk_f32 v7, v67, 0x3e38aa3b, v125
	v_max_f32_e32 v8, v4, v6
	v_max_f32_e32 v11, v7, v9
	v_max3_f32 v14, v10, v8, v11
	v_fmamk_f32 v49, v55, 0x3e38aa3b, v127
	v_fmamk_f32 v8, v68, 0x3e38aa3b, v128
	v_fmamk_f32 v10, v52, 0x3e38aa3b, v116
	v_fmamk_f32 v11, v69, 0x3e38aa3b, v129
	v_max_f32_e32 v12, v8, v10
	v_max_f32_e32 v15, v11, v13
	v_max3_f32 v50, v14, v12, v15
	v_fmamk_f32 v68, v54, 0x3e38aa3b, v126
	v_fmamk_f32 v12, v70, 0x3e38aa3b, v130
	v_fmamk_f32 v15, v71, 0x3e38aa3b, v131
	v_max_f32_e32 v14, v12, v68
	v_max_f32_e32 v48, v15, v49
	v_max3_f32 v54, v50, v14, v48
	v_fmamk_f32 v48, v56, 0x3e38aa3b, v132
	v_fmamk_f32 v53, v57, 0x3e38aa3b, v133
	v_fmamk_f32 v14, v72, 0x3e38aa3b, v134
	v_fmamk_f32 v51, v73, 0x3e38aa3b, v135
	v_max_f32_e32 v50, v14, v48
	v_max_f32_e32 v52, v51, v53
	v_max3_f32 v64, v54, v50, v52
	v_fmamk_f32 v52, v58, 0x3e38aa3b, v136
	v_fmamk_f32 v57, v59, 0x3e38aa3b, v137
	v_fmamk_f32 v50, v74, 0x3e38aa3b, v138
	v_fmamk_f32 v55, v75, 0x3e38aa3b, v139
	v_max_f32_e32 v54, v50, v52
	v_max_f32_e32 v56, v55, v57
	v_max3_f32 v66, v64, v54, v56
	v_fmamk_f32 v54, v76, 0x3e38aa3b, v140
	v_fmamk_f32 v59, v77, 0x3e38aa3b, v141
	v_fmamk_f32 v56, v60, 0x3e38aa3b, v142
	v_fmamk_f32 v65, v61, 0x3e38aa3b, v143
	v_max_f32_e32 v58, v54, v56
	v_max_f32_e32 v60, v59, v65
	v_max3_f32 v64, v66, v58, v60
	v_fmamk_f32 v58, v78, 0x3e38aa3b, v144
	v_fmamk_f32 v60, v62, 0x3e38aa3b, v146
	v_fmamk_f32 v61, v79, 0x3e38aa3b, v145
	v_fmamk_f32 v67, v63, 0x3e38aa3b, v147
	v_max_f32_e32 v62, v58, v60
	v_max_f32_e32 v63, v61, v67
	v_max3_f32 v62, v64, v62, v63
	v_add_f32_e32 v63, 0x41000000, v102
	v_cmp_gt_f32_e32 vcc, v62, v63
	s_cbranch_vccz .LBB0_288
	v_xor_b32_e32 v63, 32, v223
	v_cmp_lt_i32_e32 vcc, v63, v225
	s_nop 1
	v_cndmask_b32_e32 v63, v223, v63, vcc
	v_lshlrev_b32_e32 v63, 2, v63
	ds_bpermute_b32 v63, v63, v62
	s_waitcnt lgkmcnt(0)
	v_max3_f32 v63, v102, v62, v63
	v_sub_f32_e32 v62, v102, v63
	v_exp_f32_e32 v62, v62
	v_mov_b32_e32 v102, v63
	v_mul_f32_e32 v112, v112, v62
	v_pk_mul_f32 v[46:47], v[46:47], v[62:63] op_sel_hi:[1,0]
	v_pk_mul_f32 v[44:45], v[44:45], v[62:63] op_sel_hi:[1,0]
	v_pk_mul_f32 v[42:43], v[42:43], v[62:63] op_sel_hi:[1,0]
	v_pk_mul_f32 v[40:41], v[40:41], v[62:63] op_sel_hi:[1,0]
	v_pk_mul_f32 v[38:39], v[38:39], v[62:63] op_sel_hi:[1,0]
	v_pk_mul_f32 v[36:37], v[36:37], v[62:63] op_sel_hi:[1,0]
	v_pk_mul_f32 v[34:35], v[34:35], v[62:63] op_sel_hi:[1,0]
	v_pk_mul_f32 v[32:33], v[32:33], v[62:63] op_sel_hi:[1,0]
	v_pk_mul_f32 v[30:31], v[30:31], v[62:63] op_sel_hi:[1,0]
	v_pk_mul_f32 v[28:29], v[28:29], v[62:63] op_sel_hi:[1,0]
	v_pk_mul_f32 v[26:27], v[26:27], v[62:63] op_sel_hi:[1,0]
	v_pk_mul_f32 v[24:25], v[24:25], v[62:63] op_sel_hi:[1,0]
	v_pk_mul_f32 v[22:23], v[22:23], v[62:63] op_sel_hi:[1,0]
	v_pk_mul_f32 v[20:21], v[20:21], v[62:63] op_sel_hi:[1,0]
	v_pk_mul_f32 v[18:19], v[18:19], v[62:63] op_sel_hi:[1,0]
	v_pk_mul_f32 v[16:17], v[16:17], v[62:63] op_sel_hi:[1,0]

; #define MFMA32(a, b, c) __builtin_amdgcn_mfma_f32_32x32x16_bf16((a), (b), (c), 0, 0, 0)
; template <int MODE, int NQ, int TS, bool FAST = false> ...
;     ...
;   auto QK = [&](int slot) {
;     const char* kb_ = lds + slot * 16384;
; #pragma unroll
;     for (int nq = 0; nq < NQ; ++nq)
; #pragma unroll
;       for (int r = 0; r < 16; ++r) { s[nq][0][r] = 0.f; s[nq][1][r] = 0.f; }
; #pragma unroll
;     for (int ks = 0; ks < 4; ++ks) {
;       const bf16x8 k0 = *(const bf16x8*)(kb_ + kfo4[ks]), k1 = *(const bf16x8*)(kb_ + kfo4[ks] + 4096);
; #pragma unroll
;       for (int nq = 0; nq < NQ; ++nq) { s[nq][0] = MFMA32(k0, qf[nq][ks], s[nq][0]); s[nq][1] = MFMA32(k1, qf[nq][ks], s[nq][1]); }
;     }
;   };
;   auto SM = [&](int kt) {
; #pragma unroll
;     for (int nq = 0; nq < NQ; ++nq) {
;       f32x16& s0 = s[nq][0]; f32x16& s1 = s[nq][1];
;       float mx = -1e30f;
;       if (MODE == 1) {
;       } else if (MODE == 0 || MODE == 3) {
;         const float* tb = (const float*)(lds + TAB_OFF) + (kt * 64 + 4 * hh - (q0w + 32 * nq + r32) + TAB_ZERO);
; #pragma unroll
;         for (int r = 0; r < 16; ++r) {
;           const float va = fmaf(s0[r], C2, tb[(r & 3) + 8 * (r >> 2)]), vb = fmaf(s1[r], C2, tb[(r & 3) + 8 * (r >> 2) + 32]);
;           s0[r] = va; s1[r] = vb; mx = fmaxf(mx, fmaxf(va, vb));
;         }
.LBB0_295:
	s_and_saveexec_b64 s[0:1], s[78:79]
	s_cbranch_execz .LBB0_299
	ds_read2_b32 v[116:117], v113 offset0:40 offset1:41
	ds_read2_b32 v[118:119], v113 offset1:1
	ds_read2_b32 v[120:121], v113 offset0:32 offset1:33
	ds_read2_b32 v[122:123], v113 offset0:34 offset1:35
	ds_read2_b32 v[124:125], v113 offset0:2 offset1:3
	ds_read2_b32 v[126:127], v113 offset0:42 offset1:43
	ds_read2_b32 v[128:129], v113 offset0:8 offset1:9
	ds_read2_b32 v[130:131], v113 offset0:10 offset1:11
	ds_read2_b32 v[132:133], v113 offset0:48 offset1:49
	ds_read2_b32 v[134:135], v113 offset0:16 offset1:17
	ds_read2_b32 v[136:137], v113 offset0:18 offset1:19
	ds_read2_b32 v[138:139], v113 offset0:50 offset1:51
	ds_read2_b32 v[140:141], v113 offset0:24 offset1:25
	ds_read2_b32 v[142:143], v113 offset0:56 offset1:57
	ds_read2_b32 v[144:145], v113 offset0:26 offset1:27
	ds_read2_b32 v[146:147], v113 offset0:58 offset1:59
	s_lshl_b32 s7, s8, 14
	v_or_b32_e32 v0, s7, v111
	ds_read_b128 v[2:5], v0
	ds_read_b128 v[6:9], v0 offset:4096
	v_or_b32_e32 v0, s7, v110
	s_waitcnt lgkmcnt(0)
	v_mfma_f32_32x32x16_bf16 v[64:79], v[2:5], v[80:83], 0
	v_mfma_f32_32x32x16_bf16 v[48:63], v[6:9], v[80:83], 0
	ds_read_b128 v[2:5], v0
	ds_read_b128 v[6:9], v0 offset:4096
	v_or_b32_e32 v0, s7, v109
	s_waitcnt lgkmcnt(0)
	v_mfma_f32_32x32x16_bf16 v[64:79], v[2:5], v[84:87], v[64:79]
	v_mfma_f32_32x32x16_bf16 v[48:63], v[6:9], v[84:87], v[48:63]
	ds_read_b128 v[2:5], v0
	ds_read_b128 v[6:9], v0 offset:4096
	v_or_b32_e32 v0, s7, v97
	s_waitcnt lgkmcnt(0)
	v_mfma_f32_32x32x16_bf16 v[64:79], v[2:5], v[88:91], v[64:79]
	v_mfma_f32_32x32x16_bf16 v[48:63], v[6:9], v[88:91], v[48:63]
	ds_read_b128 v[2:5], v0
	ds_read_b128 v[6:9], v0 offset:4096
	s_waitcnt lgkmcnt(0)
	v_mfma_f32_32x32x16_bf16 v[64:79], v[2:5], v[92:95], v[64:79]
	v_mfma_f32_32x32x16_bf16 v[48:63], v[6:9], v[92:95], v[48:63]
	s_nop 10
	v_fmamk_f32 v0, v64, 0x3e38aa3b, v118
	v_fmamk_f32 v3, v65, 0x3e38aa3b, v119
	v_fmamk_f32 v2, v48, 0x3e38aa3b, v120
	v_fmamk_f32 v5, v49, 0x3e38aa3b, v121
	v_max_f32_e32 v4, v0, v2
	v_max_f32_e32 v6, v3, v5
	v_max3_f32 v10, v4, s25, v6
	v_fmamk_f32 v9, v51, 0x3e38aa3b, v123
	v_fmamk_f32 v13, v53, 0x3e38aa3b, v117
	v_fmamk_f32 v4, v66, 0x3e38aa3b, v124
	v_fmamk_f32 v6, v50, 0x3e38aa3b, v122
	v_fmamk_f32 v7, v67, 0x3e38aa3b, v125
	v_max_f32_e32 v8, v4, v6
	v_max_f32_e32 v11, v7, v9
	v_max3_f32 v14, v10, v8, v11
	v_fmamk_f32 v48, v54, 0x3e38aa3b, v126
	v_fmamk_f32 v49, v55, 0x3e38aa3b, v127
	v_fmamk_f32 v8, v68, 0x3e38aa3b, v128
	v_fmamk_f32 v10, v52, 0x3e38aa3b, v116
	v_fmamk_f32 v11, v69, 0x3e38aa3b, v129
	v_max_f32_e32 v12, v8, v10
	v_max_f32_e32 v15, v11, v13
	v_max3_f32 v50, v14, v12, v15
	v_fmamk_f32 v12, v70, 0x3e38aa3b, v130
	v_fmamk_f32 v15, v71, 0x3e38aa3b, v131
	v_max_f32_e32 v14, v12, v48
	v_max_f32_e32 v51, v15, v49
	v_max3_f32 v54, v50, v14, v51
	v_fmamk_f32 v53, v57, 0x3e38aa3b, v133
	v_fmamk_f32 v14, v72, 0x3e38aa3b, v134
	v_fmamk_f32 v50, v56, 0x3e38aa3b, v132
	v_fmamk_f32 v51, v73, 0x3e38aa3b, v135
	v_max_f32_e32 v52, v14, v50
	v_max_f32_e32 v55, v51, v53
	v_max3_f32 v64, v54, v52, v55
	v_fmamk_f32 v52, v74, 0x3e38aa3b, v136
	v_fmamk_f32 v54, v58, 0x3e38aa3b, v138
	v_fmamk_f32 v55, v75, 0x3e38aa3b, v137
	v_fmamk_f32 v57, v59, 0x3e38aa3b, v139
	v_max_f32_e32 v56, v52, v54
	v_max_f32_e32 v58, v55, v57
	v_max3_f32 v66, v64, v56, v58
	v_fmamk_f32 v56, v76, 0x3e38aa3b, v140
	v_fmamk_f32 v58, v60, 0x3e38aa3b, v142
	v_fmamk_f32 v59, v77, 0x3e38aa3b, v141
	v_fmamk_f32 v65, v61, 0x3e38aa3b, v143
	v_max_f32_e32 v60, v56, v58
	v_max_f32_e32 v61, v59, v65
	v_max3_f32 v64, v66, v60, v61
	v_fmamk_f32 v60, v78, 0x3e38aa3b, v144
	v_fmamk_f32 v62, v62, 0x3e38aa3b, v146
	v_fmamk_f32 v61, v79, 0x3e38aa3b, v145
	v_fmamk_f32 v67, v63, 0x3e38aa3b, v147
	v_max_f32_e32 v66, v60, v62
	v_max_f32_e32 v63, v61, v67
	v_max3_f32 v63, v64, v66, v63
	v_add_f32_e32 v64, 0x41000000, v102
	v_cmp_gt_f32_e32 vcc, v63, v64
	s_cbranch_vccz .LBB0_298
	v_xor_b32_e32 v64, 32, v223
	v_cmp_lt_i32_e32 vcc, v64, v225
	s_nop 1
	v_cndmask_b32_e32 v64, v223, v64, vcc
	v_lshlrev_b32_e32 v64, 2, v64
	ds_bpermute_b32 v64, v64, v63
	s_waitcnt lgkmcnt(0)
	v_max3_f32 v63, v102, v63, v64
	v_sub_f32_e32 v64, v102, v63
	v_exp_f32_e32 v64, v64
	v_mov_b32_e32 v102, v63
	v_mul_f32_e32 v112, v112, v64
	v_pk_mul_f32 v[46:47], v[46:47], v[64:65] op_sel_hi:[1,0]
	v_pk_mul_f32 v[44:45], v[44:45], v[64:65] op_sel_hi:[1,0]
	v_pk_mul_f32 v[42:43], v[42:43], v[64:65] op_sel_hi:[1,0]
	v_pk_mul_f32 v[40:41], v[40:41], v[64:65] op_sel_hi:[1,0]
	v_pk_mul_f32 v[38:39], v[38:39], v[64:65] op_sel_hi:[1,0]
	v_pk_mul_f32 v[36:37], v[36:37], v[64:65] op_sel_hi:[1,0]
	v_pk_mul_f32 v[34:35], v[34:35], v[64:65] op_sel_hi:[1,0]
	v_pk_mul_f32 v[32:33], v[32:33], v[64:65] op_sel_hi:[1,0]
	v_pk_mul_f32 v[30:31], v[30:31], v[64:65] op_sel_hi:[1,0]
	v_pk_mul_f32 v[28:29], v[28:29], v[64:65] op_sel_hi:[1,0]
	v_pk_mul_f32 v[26:27], v[26:27], v[64:65] op_sel_hi:[1,0]
	v_pk_mul_f32 v[24:25], v[24:25], v[64:65] op_sel_hi:[1,0]
	v_pk_mul_f32 v[22:23], v[22:23], v[64:65] op_sel_hi:[1,0]
	v_pk_mul_f32 v[20:21], v[20:21], v[64:65] op_sel_hi:[1,0]
	v_pk_mul_f32 v[18:19], v[18:19], v[64:65] op_sel_hi:[1,0]
	v_pk_mul_f32 v[16:17], v[16:17], v[64:65] op_sel_hi:[1,0]

; template <int MODE, int NQ, int TS, bool FAST = false> ...
;     ...
;   auto QK = [&](int slot) {
;     const char* kb_ = lds + slot * 16384;
; #pragma unroll
;     for (int nq = 0; nq < NQ; ++nq)
; #pragma unroll
;       for (int r = 0; r < 16; ++r) { s[nq][0][r] = 0.f; s[nq][1][r] = 0.f; }
; #pragma unroll
;     for (int ks = 0; ks < 4; ++ks) {
;       const bf16x8 k0 = *(const bf16x8*)(kb_ + kfo4[ks]), k1 = *(const bf16x8*)(kb_ + kfo4[ks] + 4096);
; #pragma unroll
;       for (int nq = 0; nq < NQ; ++nq) { s[nq][0] = MFMA32(k0, qf[nq][ks], s[nq][0]); s[nq][1] = MFMA32(k1, qf[nq][ks], s[nq][1]); }
;     }
;   };
;   auto SM = [&](int kt) {
; #pragma unroll
;     for (int nq = 0; nq < NQ; ++nq) {
;       f32x16& s0 = s[nq][0]; f32x16& s1 = s[nq][1];
;       float mx = -1e30f;
;       if (MODE == 1) {
;       } else if (MODE == 0 || MODE == 3) {
;         const float* tb = (const float*)(lds + TAB_OFF) + (kt * 64 + 4 * hh - (q0w + 32 * nq + r32) + TAB_ZERO);
; #pragma unroll
;         for (int r = 0; r < 16; ++r) {
;           const float va = fmaf(s0[r], C2, tb[(r & 3) + 8 * (r >> 2)]), vb = fmaf(s1[r], C2, tb[(r & 3) + 8 * (r >> 2) + 32]);
;           s0[r] = va; s1[r] = vb; mx = fmaxf(mx, fmaxf(va, vb));
;         }
;       } else {
;         const float* tb = (const float*)(lds + TAB_OFF) + (wave & 3) * 512 + (kt * 64 + 4 * hh - (q0w + 32 * nq + r32) + 256);
; #pragma unroll
;         for (int r = 0; r < 16; ++r) {
;           const float va = fmaf(s0[r], C2, tb[(r & 3) + 8 * (r >> 2)]), vb = fmaf(s1[r], C2, tb[(r & 3) + 8 * (r >> 2) + 32]);
;           s0[r] = va; s1[r] = vb; mx = fmaxf(mx, fmaxf(va, vb));
;         }
;       }
;       float mn;
;       if (MODE == 1) {
;         mn = sink2;
;       } else {
;         if (__any(mx > m2[nq] + 8.f)) {
;           mx = fmaxf(mx, __shfl_xor(mx, 32));
;           mn = fmaxf(m2[nq], mx);
;           const float alpha = __builtin_amdgcn_exp2f(m2[nq] - mn);
;           l[nq] *= alpha;
; #pragma unroll
;           for (int r = 0; r < 16; ++r) { o[nq][0][r] *= alpha; o[nq][1][r] *= alpha; }
;           m2[nq] = mn;
;         }
;         mn = m2[nq];
;     ...
;     { const int tn = (kt + 4 < ktl) ? kt + 4 : ktl; int s4 = slot + 4; if (s4 >= NS) s4 -= NS; ATT_ISSUE(tn, s4); }
;     const bool act = tile_active(kt);
;     if (!g2) {
;       if (act) { QK(slot); SM(kt); PV(slot); }
.LBB0_392:
	s_min_i32 s7, s8, s14
	s_cmp_gt_i32 s0, 1
	s_mov_b32 s6, s0
	s_cselect_b32 s0, -2, 4
	s_add_i32 s12, s0, s6
	v_mad_i64_i32 v[50:51], s[0:1], s7, v237, v[84:85]
	s_lshl_b32 s0, s12, 14
	s_add_i32 s12, s15, s0
	v_lshl_add_u64 v[50:51], v[50:51], 0, s[60:61]
	s_mov_b32 m0, s12
	s_nop 0
	global_load_lds_dwordx4 v[50:51], off
	v_mad_i64_i32 v[50:51], s[0:1], s7, v237, v[86:87]
	v_lshl_add_u64 v[50:51], v[50:51], 0, s[58:59]
	s_add_i32 m0, s12, 0x2000
	s_add_i32 s7, s30, 64
	global_load_lds_dwordx4 v[50:51], off
	s_add_i32 s0, s30, 0x7f
	v_cmp_ge_i32_e32 vcc, s0, v101
	v_cmp_le_i32_e64 s[0:1], s7, v102
	s_and_b64 s[26:27], vcc, s[0:1]
	s_and_saveexec_b64 s[0:1], s[40:41]
	s_xor_b64 s[0:1], exec, s[0:1]
	s_cbranch_execz .LBB0_398
	s_and_saveexec_b64 s[78:79], s[26:27]
	s_cbranch_execz .LBB0_397
	ds_read2_b32 v[108:109], v103 offset1:1
	ds_read2_b32 v[110:111], v103 offset0:32 offset1:33
	ds_read2_b32 v[112:113], v103 offset0:34 offset1:35
	ds_read2_b32 v[114:115], v103 offset0:2 offset1:3
	ds_read2_b32 v[116:117], v103 offset0:8 offset1:9
	ds_read2_b32 v[118:119], v103 offset0:40 offset1:41
	ds_read2_b32 v[120:121], v103 offset0:10 offset1:11
	ds_read2_b32 v[122:123], v103 offset0:42 offset1:43
	ds_read2_b32 v[124:125], v103 offset0:16 offset1:17
	ds_read2_b32 v[126:127], v103 offset0:48 offset1:49
	ds_read2_b32 v[128:129], v103 offset0:18 offset1:19
	ds_read2_b32 v[130:131], v103 offset0:50 offset1:51
	ds_read2_b32 v[132:133], v103 offset0:24 offset1:25
	ds_read2_b32 v[134:135], v103 offset0:56 offset1:57
	ds_read2_b32 v[136:137], v103 offset0:26 offset1:27
	ds_read2_b32 v[138:139], v103 offset0:58 offset1:59
	s_lshl_b32 s12, s6, 14
	v_or_b32_e32 v0, s12, v100
	ds_read_b128 v[34:37], v0
	ds_read_b128 v[38:41], v0 offset:4096
	v_or_b32_e32 v0, s12, v99
	ds_read_b128 v[88:91], v0
	ds_read_b128 v[104:107], v0 offset:4096
	v_or_b32_e32 v0, s12, v98
	s_waitcnt lgkmcnt(0)
	v_mfma_f32_32x32x16_bf16 v[50:65], v[34:37], v[66:69], 0
	v_mfma_f32_32x32x16_bf16 v[34:49], v[38:41], v[66:69], 0
	v_mfma_f32_32x32x16_bf16 v[50:65], v[88:91], v[70:73], v[50:65]
	v_mfma_f32_32x32x16_bf16 v[34:49], v[104:107], v[70:73], v[34:49]
	ds_read_b128 v[88:91], v0
	ds_read_b128 v[104:107], v0 offset:4096
	v_or_b32_e32 v0, s12, v97
	s_waitcnt lgkmcnt(0)
	v_mfma_f32_32x32x16_bf16 v[50:65], v[88:91], v[74:77], v[50:65]
	v_mfma_f32_32x32x16_bf16 v[34:49], v[104:107], v[74:77], v[34:49]
	ds_read_b128 v[88:91], v0
	ds_read_b128 v[104:107], v0 offset:4096
	s_waitcnt lgkmcnt(0)
	v_mfma_f32_32x32x16_bf16 v[50:65], v[88:91], v[78:81], v[50:65]
	v_mfma_f32_32x32x16_bf16 v[34:49], v[104:107], v[78:81], v[34:49]
	s_nop 10
	v_fmamk_f32 v0, v50, 0x3e38aa3b, v108
	v_fmamk_f32 v89, v51, 0x3e38aa3b, v109
	v_fmamk_f32 v88, v34, 0x3e38aa3b, v110
	v_fmamk_f32 v91, v35, 0x3e38aa3b, v111
	v_max_f32_e32 v34, v0, v88
	v_max_f32_e32 v35, v89, v91
	v_max3_f32 v90, v34, s23, v35
	v_fmamk_f32 v50, v36, 0x3e38aa3b, v112
	v_fmamk_f32 v51, v37, 0x3e38aa3b, v113
	v_fmamk_f32 v34, v52, 0x3e38aa3b, v114
	v_fmamk_f32 v35, v53, 0x3e38aa3b, v115
	v_max_f32_e32 v36, v34, v50
	v_max_f32_e32 v37, v35, v51
	v_max3_f32 v90, v90, v36, v37
	v_fmamk_f32 v36, v54, 0x3e38aa3b, v116
	v_fmamk_f32 v52, v38, 0x3e38aa3b, v118
	v_fmamk_f32 v37, v55, 0x3e38aa3b, v117
	v_fmamk_f32 v53, v39, 0x3e38aa3b, v119
	v_max_f32_e32 v38, v36, v52
	v_max_f32_e32 v39, v37, v53
	v_max3_f32 v104, v90, v38, v39
	v_fmamk_f32 v38, v56, 0x3e38aa3b, v120
	v_fmamk_f32 v90, v40, 0x3e38aa3b, v122
	v_fmamk_f32 v39, v57, 0x3e38aa3b, v121
	v_fmamk_f32 v55, v41, 0x3e38aa3b, v123
	v_max_f32_e32 v40, v38, v90
	v_max_f32_e32 v41, v39, v55
	v_max3_f32 v104, v104, v40, v41
	v_fmamk_f32 v40, v58, 0x3e38aa3b, v124
	v_fmamk_f32 v54, v42, 0x3e38aa3b, v126
	v_fmamk_f32 v41, v59, 0x3e38aa3b, v125
	v_fmamk_f32 v57, v43, 0x3e38aa3b, v127
	v_max_f32_e32 v42, v40, v54
	v_max_f32_e32 v43, v41, v57
	v_max3_f32 v104, v104, v42, v43
	v_fmamk_f32 v42, v60, 0x3e38aa3b, v128
	v_fmamk_f32 v56, v44, 0x3e38aa3b, v130
	v_fmamk_f32 v43, v61, 0x3e38aa3b, v129
	v_fmamk_f32 v59, v45, 0x3e38aa3b, v131
	v_max_f32_e32 v44, v42, v56
	v_max_f32_e32 v45, v43, v59
	v_max3_f32 v104, v104, v44, v45
	v_fmamk_f32 v44, v62, 0x3e38aa3b, v132
	v_fmamk_f32 v58, v46, 0x3e38aa3b, v134
	v_fmamk_f32 v45, v63, 0x3e38aa3b, v133
	v_fmamk_f32 v61, v47, 0x3e38aa3b, v135
	v_max_f32_e32 v46, v44, v58
	v_max_f32_e32 v47, v45, v61
	v_max3_f32 v60, v104, v46, v47
	v_fmamk_f32 v46, v64, 0x3e38aa3b, v136
	v_fmamk_f32 v48, v48, 0x3e38aa3b, v138
	v_fmamk_f32 v47, v65, 0x3e38aa3b, v137
	v_fmamk_f32 v63, v49, 0x3e38aa3b, v139
	v_max_f32_e32 v62, v46, v48
	v_max_f32_e32 v49, v47, v63
	v_max3_f32 v49, v60, v62, v49
	v_add_f32_e32 v60, 0x41000000, v94
	v_cmp_gt_f32_e32 vcc, v49, v60
	s_cbranch_vccz .LBB0_396
	ds_bpermute_b32 v60, v163, v49
	s_waitcnt lgkmcnt(0)
	v_max3_f32 v49, v94, v49, v60
	v_sub_f32_e32 v60, v94, v49
	v_exp_f32_e32 v60, v60
	v_mov_b32_e32 v94, v49
	v_mul_f32_e32 v92, v92, v60
	v_pk_mul_f32 v[32:33], v[32:33], v[60:61] op_sel_hi:[1,0]
	v_pk_mul_f32 v[30:31], v[30:31], v[60:61] op_sel_hi:[1,0]
	v_pk_mul_f32 v[28:29], v[28:29], v[60:61] op_sel_hi:[1,0]
	v_pk_mul_f32 v[26:27], v[26:27], v[60:61] op_sel_hi:[1,0]
	v_pk_mul_f32 v[24:25], v[24:25], v[60:61] op_sel_hi:[1,0]
	v_pk_mul_f32 v[22:23], v[22:23], v[60:61] op_sel_hi:[1,0]
	v_pk_mul_f32 v[20:21], v[20:21], v[60:61] op_sel_hi:[1,0]
	v_pk_mul_f32 v[18:19], v[18:19], v[60:61] op_sel_hi:[1,0]
	v_pk_mul_f32 v[16:17], v[16:17], v[60:61] op_sel_hi:[1,0]
	v_pk_mul_f32 v[14:15], v[14:15], v[60:61] op_sel_hi:[1,0]
	v_pk_mul_f32 v[12:13], v[12:13], v[60:61] op_sel_hi:[1,0]
	v_pk_mul_f32 v[10:11], v[10:11], v[60:61] op_sel_hi:[1,0]
	v_pk_mul_f32 v[8:9], v[8:9], v[60:61] op_sel_hi:[1,0]
	v_pk_mul_f32 v[6:7], v[6:7], v[60:61] op_sel_hi:[1,0]
	v_pk_mul_f32 v[4:5], v[4:5], v[60:61] op_sel_hi:[1,0]
	v_pk_mul_f32 v[2:3], v[2:3], v[60:61] op_sel_hi:[1,0]

; #define MFMA32(a, b, c) __builtin_amdgcn_mfma_f32_32x32x16_bf16((a), (b), (c), 0, 0, 0)
; template <int MODE, int NQ, int TS, bool FAST = false> ...
;     ...
;   auto QK = [&](int slot) {
;     const char* kb_ = lds + slot * 16384;
; #pragma unroll
;     for (int nq = 0; nq < NQ; ++nq)
; #pragma unroll
;       for (int r = 0; r < 16; ++r) { s[nq][0][r] = 0.f; s[nq][1][r] = 0.f; }
; #pragma unroll
;     for (int ks = 0; ks < 4; ++ks) {
;       const bf16x8 k0 = *(const bf16x8*)(kb_ + kfo4[ks]), k1 = *(const bf16x8*)(kb_ + kfo4[ks] + 4096);
; #pragma unroll
;       for (int nq = 0; nq < NQ; ++nq) { s[nq][0] = MFMA32(k0, qf[nq][ks], s[nq][0]); s[nq][1] = MFMA32(k1, qf[nq][ks], s[nq][1]); }
;     }
;   };
;   auto SM = [&](int kt) {
; #pragma unroll
;     for (int nq = 0; nq < NQ; ++nq) {
;       f32x16& s0 = s[nq][0]; f32x16& s1 = s[nq][1];
;       float mx = -1e30f;
;       if (MODE == 1) {
;       } else if (MODE == 0 || MODE == 3) {
;         const float* tb = (const float*)(lds + TAB_OFF) + (kt * 64 + 4 * hh - (q0w + 32 * nq + r32) + TAB_ZERO);
; #pragma unroll
;         for (int r = 0; r < 16; ++r) {
;           const float va = fmaf(s0[r], C2, tb[(r & 3) + 8 * (r >> 2)]), vb = fmaf(s1[r], C2, tb[(r & 3) + 8 * (r >> 2) + 32]);
;           s0[r] = va; s1[r] = vb; mx = fmaxf(mx, fmaxf(va, vb));
;         }
;       } else {
;         const float* tb = (const float*)(lds + TAB_OFF) + (wave & 3) * 512 + (kt * 64 + 4 * hh - (q0w + 32 * nq + r32) + 256);
; #pragma unroll
;         for (int r = 0; r < 16; ++r) {
;           const float va = fmaf(s0[r], C2, tb[(r & 3) + 8 * (r >> 2)]), vb = fmaf(s1[r], C2, tb[(r & 3) + 8 * (r >> 2) + 32]);
;           s0[r] = va; s1[r] = vb; mx = fmaxf(mx, fmaxf(va, vb));
;         }
;       }
;       float mn;
;       if (MODE == 1) {
;         mn = sink2;
;       } else {
;         if (__any(mx > m2[nq] + 8.f)) {
;           mx = fmaxf(mx, __shfl_xor(mx, 32));
;           mn = fmaxf(m2[nq], mx);
;           const float alpha = __builtin_amdgcn_exp2f(m2[nq] - mn);
;           l[nq] *= alpha;
; #pragma unroll
;           for (int r = 0; r < 16; ++r) { o[nq][0][r] *= alpha; o[nq][1][r] *= alpha; }
;           m2[nq] = mn;
;         }
;         mn = m2[nq];
;     ...
;       if (kt > kt0 && tile_active(kt - 1)) PV(sp);
;       if (act) { QK(slot); SM(kt); }
.LBB0_403:
	s_and_saveexec_b64 s[0:1], s[26:27]
	s_cbranch_execz .LBB0_407
	ds_read2_b32 v[108:109], v103 offset1:1
	ds_read2_b32 v[110:111], v103 offset0:32 offset1:33
	ds_read2_b32 v[112:113], v103 offset0:34 offset1:35
	ds_read2_b32 v[114:115], v103 offset0:2 offset1:3
	ds_read2_b32 v[116:117], v103 offset0:8 offset1:9
	ds_read2_b32 v[118:119], v103 offset0:40 offset1:41
	ds_read2_b32 v[120:121], v103 offset0:10 offset1:11
	ds_read2_b32 v[122:123], v103 offset0:42 offset1:43
	ds_read2_b32 v[124:125], v103 offset0:16 offset1:17
	ds_read2_b32 v[126:127], v103 offset0:48 offset1:49
	ds_read2_b32 v[128:129], v103 offset0:18 offset1:19
	ds_read2_b32 v[130:131], v103 offset0:50 offset1:51
	ds_read2_b32 v[132:133], v103 offset0:24 offset1:25
	ds_read2_b32 v[134:135], v103 offset0:56 offset1:57
	ds_read2_b32 v[136:137], v103 offset0:26 offset1:27
	ds_read2_b32 v[138:139], v103 offset0:58 offset1:59
	s_lshl_b32 s9, s6, 14
	v_or_b32_e32 v0, s9, v100
	ds_read_b128 v[34:37], v0
	ds_read_b128 v[38:41], v0 offset:4096
	v_or_b32_e32 v0, s9, v99
	ds_read_b128 v[88:91], v0
	ds_read_b128 v[104:107], v0 offset:4096
	v_or_b32_e32 v0, s9, v98
	s_waitcnt lgkmcnt(0)
	v_mfma_f32_32x32x16_bf16 v[50:65], v[34:37], v[66:69], 0
	v_mfma_f32_32x32x16_bf16 v[34:49], v[38:41], v[66:69], 0
	v_mfma_f32_32x32x16_bf16 v[50:65], v[88:91], v[70:73], v[50:65]
	v_mfma_f32_32x32x16_bf16 v[34:49], v[104:107], v[70:73], v[34:49]
	ds_read_b128 v[88:91], v0
	ds_read_b128 v[104:107], v0 offset:4096
	v_or_b32_e32 v0, s9, v97
	s_waitcnt lgkmcnt(0)
	v_mfma_f32_32x32x16_bf16 v[50:65], v[88:91], v[74:77], v[50:65]
	v_mfma_f32_32x32x16_bf16 v[34:49], v[104:107], v[74:77], v[34:49]
	ds_read_b128 v[88:91], v0
	ds_read_b128 v[104:107], v0 offset:4096
	s_waitcnt lgkmcnt(0)
	v_mfma_f32_32x32x16_bf16 v[50:65], v[88:91], v[78:81], v[50:65]
	v_mfma_f32_32x32x16_bf16 v[34:49], v[104:107], v[78:81], v[34:49]
	s_nop 10
	v_fmamk_f32 v0, v50, 0x3e38aa3b, v108
	v_fmamk_f32 v89, v51, 0x3e38aa3b, v109
	v_fmamk_f32 v88, v34, 0x3e38aa3b, v110
	v_fmamk_f32 v91, v35, 0x3e38aa3b, v111
	v_max_f32_e32 v34, v0, v88
	v_max_f32_e32 v35, v89, v91
	v_max3_f32 v90, v34, s23, v35
	v_fmamk_f32 v50, v36, 0x3e38aa3b, v112
	v_fmamk_f32 v51, v37, 0x3e38aa3b, v113
	v_fmamk_f32 v34, v52, 0x3e38aa3b, v114
	v_fmamk_f32 v35, v53, 0x3e38aa3b, v115
	v_max_f32_e32 v36, v34, v50
	v_max_f32_e32 v37, v35, v51
	v_max3_f32 v90, v90, v36, v37
	v_fmamk_f32 v36, v54, 0x3e38aa3b, v116
	v_fmamk_f32 v52, v38, 0x3e38aa3b, v118
	v_fmamk_f32 v37, v55, 0x3e38aa3b, v117
	v_fmamk_f32 v53, v39, 0x3e38aa3b, v119
	v_max_f32_e32 v38, v36, v52
	v_max_f32_e32 v39, v37, v53
	v_max3_f32 v90, v90, v38, v39
	v_fmamk_f32 v38, v56, 0x3e38aa3b, v120
	v_fmamk_f32 v54, v40, 0x3e38aa3b, v122
	v_fmamk_f32 v39, v57, 0x3e38aa3b, v121
	v_fmamk_f32 v55, v41, 0x3e38aa3b, v123
	v_max_f32_e32 v40, v38, v54
	v_max_f32_e32 v41, v39, v55
	v_max3_f32 v90, v90, v40, v41
	v_fmamk_f32 v40, v58, 0x3e38aa3b, v124
	v_fmamk_f32 v56, v42, 0x3e38aa3b, v126
	v_fmamk_f32 v41, v59, 0x3e38aa3b, v125
	v_fmamk_f32 v57, v43, 0x3e38aa3b, v127
	v_max_f32_e32 v42, v40, v56
	v_max_f32_e32 v43, v41, v57
	v_max3_f32 v90, v90, v42, v43
	v_fmamk_f32 v42, v60, 0x3e38aa3b, v128
	v_fmamk_f32 v58, v44, 0x3e38aa3b, v130
	v_fmamk_f32 v43, v61, 0x3e38aa3b, v129
	v_fmamk_f32 v59, v45, 0x3e38aa3b, v131
	v_max_f32_e32 v44, v42, v58
	v_max_f32_e32 v45, v43, v59
	v_max3_f32 v90, v90, v44, v45
	v_fmamk_f32 v44, v62, 0x3e38aa3b, v132
	v_fmamk_f32 v60, v46, 0x3e38aa3b, v134
	v_fmamk_f32 v45, v63, 0x3e38aa3b, v133
	v_fmamk_f32 v61, v47, 0x3e38aa3b, v135
	v_max_f32_e32 v46, v44, v60
	v_max_f32_e32 v47, v45, v61
	v_max3_f32 v90, v90, v46, v47
	v_fmamk_f32 v46, v64, 0x3e38aa3b, v136
	v_fmamk_f32 v48, v48, 0x3e38aa3b, v138
	v_fmamk_f32 v47, v65, 0x3e38aa3b, v137
	v_fmamk_f32 v63, v49, 0x3e38aa3b, v139
	v_max_f32_e32 v62, v46, v48
	v_max_f32_e32 v49, v47, v63
	v_max3_f32 v49, v90, v62, v49
	v_add_f32_e32 v62, 0x41000000, v94
	v_cmp_gt_f32_e32 vcc, v49, v62
	s_cbranch_vccz .LBB0_406
	ds_bpermute_b32 v62, v163, v49
	s_waitcnt lgkmcnt(0)
	v_max3_f32 v49, v94, v49, v62
	v_sub_f32_e32 v62, v94, v49
	v_exp_f32_e32 v62, v62
	v_mov_b32_e32 v94, v49
	v_mul_f32_e32 v92, v92, v62
	v_pk_mul_f32 v[32:33], v[32:33], v[62:63] op_sel_hi:[1,0]
	v_pk_mul_f32 v[30:31], v[30:31], v[62:63] op_sel_hi:[1,0]
	v_pk_mul_f32 v[28:29], v[28:29], v[62:63] op_sel_hi:[1,0]
	v_pk_mul_f32 v[26:27], v[26:27], v[62:63] op_sel_hi:[1,0]
	v_pk_mul_f32 v[24:25], v[24:25], v[62:63] op_sel_hi:[1,0]
	v_pk_mul_f32 v[22:23], v[22:23], v[62:63] op_sel_hi:[1,0]
	v_pk_mul_f32 v[20:21], v[20:21], v[62:63] op_sel_hi:[1,0]
	v_pk_mul_f32 v[18:19], v[18:19], v[62:63] op_sel_hi:[1,0]
	v_pk_mul_f32 v[16:17], v[16:17], v[62:63] op_sel_hi:[1,0]
	v_pk_mul_f32 v[14:15], v[14:15], v[62:63] op_sel_hi:[1,0]
	v_pk_mul_f32 v[12:13], v[12:13], v[62:63] op_sel_hi:[1,0]
	v_pk_mul_f32 v[10:11], v[10:11], v[62:63] op_sel_hi:[1,0]
	v_pk_mul_f32 v[8:9], v[8:9], v[62:63] op_sel_hi:[1,0]
	v_pk_mul_f32 v[6:7], v[6:7], v[62:63] op_sel_hi:[1,0]
	v_pk_mul_f32 v[4:5], v[4:5], v[62:63] op_sel_hi:[1,0]
	v_pk_mul_f32 v[2:3], v[2:3], v[62:63] op_sel_hi:[1,0]
